# code placement: GEMM K-loop heads (P1, P5 x3, P6) pinned to 64-byte boundaries with .p2align 6; on top of v23
# speedup vs baseline: 1.0128x; 1.0069x over previous
; template <class Epi, class Sched, bool ALIGN_EPI = false, bool SP2 = false>
; __device__ __forceinline__ void gemm_phase(PG8_LAS unsigned char* lds, const Gemm g, const Sched& S, const Epi& E, int wid_in) {
;     ...
;         const bool has_next = S.next(ui + 1, nxt);
;         const char* nA = has_next ? (const char*)g.A + (size_t)nxt.pm * tstep : cA; const char* nB = has_next ? (const char*)g.Bt + (size_t)nxt.pn * tstep : cB;
;         for (int t = 0; t < nt; t += 2) {
;             const bool last = (t == nt - 2);
;             if constexpr (Epi::HAS_MID) { if (t == nt / 2) E.mid(acc, cur, wr, wc, fr, fq); }
;             const char* a1 = cA + (size_t)(t + 1) * kstep;
;             const char* a2 = last ? nA : cA + (size_t)(t + 2) * kstep; const char* b2 = last ? nB : cB + (size_t)(t + 2) * kstep;
;     ...
; #pragma unroll
;         for (int a = 0; a < 2; ++a)
; #pragma unroll
;             for (int b = 0; b < 2; ++b)
; #pragma unroll
;                 for (int m = 0; m < 4; ++m)
; #pragma unroll
;                     for (int n = 0; n < 2; ++n) acc[a][b][m][n] = (f32x4){0.f, 0.f, 0.f, 0.f};
.LBB0_226:
	s_ashr_i32 s83, s82, 31
	s_lshl_b64 s[84:85], s[82:83], 19
	s_add_u32 s84, s8, s84
	s_addc_u32 s85, s9, s85
	s_and_b64 s[86:87], s[0:1], exec
	s_cselect_b32 s3, s85, s69
	s_cselect_b32 s5, s84, s68
	s_ashr_i32 s81, s80, 31
	s_lshl_b64 s[86:87], s[80:81], 19
	s_add_u32 s86, s13, s86
	s_addc_u32 s87, s33, s87
	s_and_b64 s[90:91], s[0:1], exec
	s_cselect_b32 s81, s87, s89
	s_cselect_b32 s83, s86, s88
	s_add_u32 s68, s68, 0x40080
	s_addc_u32 s69, s69, 0
	s_add_u32 s92, s88, 0x100
	v_mov_b32_e32 v0, 0
	s_addc_u32 s93, s89, 0
	s_mov_b32 s94, -2
	v_mov_b32_e32 v1, v0
	v_mov_b32_e32 v2, v0
	v_mov_b32_e32 v3, v0
	v_mov_b32_e32 v4, v0
	v_mov_b32_e32 v5, v0
	v_mov_b32_e32 v6, v0
	v_mov_b32_e32 v7, v0
	v_mov_b32_e32 v16, v0
	v_mov_b32_e32 v17, v0
	v_mov_b32_e32 v18, v0
	v_mov_b32_e32 v19, v0
	v_mov_b32_e32 v20, v0
	v_mov_b32_e32 v21, v0
	v_mov_b32_e32 v22, v0
	v_mov_b32_e32 v23, v0
	v_mov_b32_e32 v32, v0
	v_mov_b32_e32 v33, v0
	v_mov_b32_e32 v34, v0
	v_mov_b32_e32 v35, v0
	v_mov_b32_e32 v36, v0
	v_mov_b32_e32 v37, v0
	v_mov_b32_e32 v38, v0
	v_mov_b32_e32 v39, v0
	v_mov_b32_e32 v48, v0
	v_mov_b32_e32 v49, v0
	v_mov_b32_e32 v50, v0
	v_mov_b32_e32 v51, v0
	v_mov_b32_e32 v52, v0
	v_mov_b32_e32 v53, v0
	v_mov_b32_e32 v54, v0
	v_mov_b32_e32 v55, v0
	v_mov_b32_e32 v8, v0
	v_mov_b32_e32 v9, v0
	v_mov_b32_e32 v10, v0
	v_mov_b32_e32 v11, v0
	v_mov_b32_e32 v12, v0
	v_mov_b32_e32 v13, v0
	v_mov_b32_e32 v14, v0
	v_mov_b32_e32 v15, v0
	v_mov_b32_e32 v24, v0
	v_mov_b32_e32 v25, v0
	v_mov_b32_e32 v26, v0
	v_mov_b32_e32 v27, v0
	v_mov_b32_e32 v28, v0
	v_mov_b32_e32 v29, v0
	v_mov_b32_e32 v30, v0
	v_mov_b32_e32 v31, v0
	v_mov_b32_e32 v40, v0
	v_mov_b32_e32 v41, v0
	v_mov_b32_e32 v42, v0
	v_mov_b32_e32 v43, v0
	v_mov_b32_e32 v44, v0
	v_mov_b32_e32 v45, v0
	v_mov_b32_e32 v46, v0
	v_mov_b32_e32 v47, v0
	v_mov_b32_e32 v56, v0
	v_mov_b32_e32 v57, v0
	v_mov_b32_e32 v58, v0
	v_mov_b32_e32 v59, v0
	v_mov_b32_e32 v60, v0
	v_mov_b32_e32 v61, v0
	v_mov_b32_e32 v62, v0
	v_mov_b32_e32 v63, v0
	v_mov_b32_e32 v64, v0
	v_mov_b32_e32 v65, v0
	v_mov_b32_e32 v66, v0
	v_mov_b32_e32 v67, v0
	v_mov_b32_e32 v68, v0
	v_mov_b32_e32 v69, v0
	v_mov_b32_e32 v70, v0
	v_mov_b32_e32 v71, v0
	v_mov_b32_e32 v80, v0
	v_mov_b32_e32 v81, v0
	v_mov_b32_e32 v82, v0
	v_mov_b32_e32 v83, v0
	v_mov_b32_e32 v84, v0
	v_mov_b32_e32 v85, v0
	v_mov_b32_e32 v86, v0
	v_mov_b32_e32 v87, v0
	v_mov_b32_e32 v96, v0
	v_mov_b32_e32 v97, v0
	v_mov_b32_e32 v98, v0
	v_mov_b32_e32 v99, v0
	v_mov_b32_e32 v100, v0
	v_mov_b32_e32 v101, v0
	v_mov_b32_e32 v102, v0
	v_mov_b32_e32 v103, v0
	v_mov_b32_e32 v112, v0
	v_mov_b32_e32 v113, v0
	v_mov_b32_e32 v114, v0
	v_mov_b32_e32 v115, v0
	v_mov_b32_e32 v116, v0
	v_mov_b32_e32 v117, v0
	v_mov_b32_e32 v118, v0
	v_mov_b32_e32 v119, v0
	v_mov_b32_e32 v72, v0
	v_mov_b32_e32 v73, v0
	v_mov_b32_e32 v74, v0
	v_mov_b32_e32 v75, v0
	v_mov_b32_e32 v76, v0
	v_mov_b32_e32 v77, v0
	v_mov_b32_e32 v78, v0
	v_mov_b32_e32 v79, v0
	v_mov_b32_e32 v88, v0
	v_mov_b32_e32 v89, v0
	v_mov_b32_e32 v90, v0
	v_mov_b32_e32 v91, v0
	v_mov_b32_e32 v92, v0
	v_mov_b32_e32 v93, v0
	v_mov_b32_e32 v94, v0
	v_mov_b32_e32 v95, v0
	v_mov_b32_e32 v104, v0
	v_mov_b32_e32 v105, v0
	v_mov_b32_e32 v106, v0
	v_mov_b32_e32 v107, v0
	v_mov_b32_e32 v108, v0
	v_mov_b32_e32 v109, v0
	v_mov_b32_e32 v110, v0
	v_mov_b32_e32 v111, v0
	v_mov_b32_e32 v120, v0
	v_mov_b32_e32 v121, v0
	v_mov_b32_e32 v122, v0
	v_mov_b32_e32 v123, v0
	v_mov_b32_e32 v124, v0
	v_mov_b32_e32 v125, v0
	v_mov_b32_e32 v126, v0
	v_mov_b32_e32 v127, v0
	.p2align	6

; #define PG8_STAGE(bufoff, gbase, voff) do { _Pragma("unroll") for (int _i = 0; _i < 2; ++_i) \
;         __builtin_amdgcn_global_load_lds((const unsigned*)((const char*)(gbase) + (voff)[_i]), (PG8_LAS unsigned*)(lds + (bufoff) + ldsw + _i * 8192), 16, 0, 0); } while (0)
; #define PG8_WAIT_V(n) asm volatile("s_waitcnt vmcnt(" #n ")" ::: "memory")
; #define PG8_BAR __builtin_amdgcn_s_barrier()
; template <int ROT, class Epi0, class Epi1, class Late, class Post0>
; __device__ __forceinline__ void gemm_phase_pair(PG8_LAS unsigned char* lds, const Gemm g0, const Gemm g1, const Unit u, const Epi0& E0, const Epi1& E1, int wid_in, const Late& late, const Post0& post0) {
;     ...
;     const int aoff = lds_byte(wr * 64 + fr, fq * 8), boff = lds_byte(wc * 32 + fr, fq * 8);
;     f32x4 acc[2][2][4][2];
; #pragma unroll
;     for (int a = 0; a < 2; ++a)
; #pragma unroll
;         for (int b = 0; b < 2; ++b)
; #pragma unroll
;             for (int m = 0; m < 4; ++m)
; #pragma unroll
;                 for (int n = 0; n < 2; ++n) acc[a][b][m][n] = (f32x4){0.f, 0.f, 0.f, 0.f};
;     ...
;     PG8_STAGE(PG8_SB(0, 0), cB + PG8_KT(0), vB0); PG8_STAGE(PG8_SB(0, 1), cB + hs0 + PG8_KT(0), vB0); PG8_STAGE(PG8_SA(0, 0), cA + PG8_KT(0), vA0); PG8_STAGE(PG8_SA(0, 1), cA + hs0 + PG8_KT(0), vA0);
;     if (wr == 1) PG8_BAR;
;     PG8_WAIT_V(2); PG8_BAR;
;     PG8_STAGE(PG8_SB(1, 0), cB + PG8_KT(1), vB0); PG8_STAGE(PG8_SA(1, 0), cA + PG8_KT(1), vA0); PG8_STAGE(PG8_SB(1, 1), cB + hs0 + PG8_KT(1), vB0);
;     PG8_WAIT_V(6); PG8_BAR;
.LBB0_846:
	v_readlane_b32 s7, v252, 5
	s_lshl_b32 s7, s7, 5
	s_and_b32 s52, s7, 0x60
	s_lshl_b32 s12, s6, 6
	v_ashrrev_i32_e32 v1, 6, v143
	s_lshr_b32 s7, s52, 3
	s_lshl_b32 s6, s6, 13
	v_lshl_add_u32 v12, v1, 10, s6
	v_add_lshl_u32 v1, v1, s7, 10
	s_mov_b64 s[6:7], 0x880
	s_add_i32 m0, s40, 0x18000
	v_lshl_add_u64 v[2:3], v[2:3], 0, s[6:7]
	s_waitcnt vmcnt(2)
	s_barrier
	global_load_lds_dwordx4 v[2:3], off
	v_lshl_add_u64 v[2:3], v[4:5], 0, s[6:7]
	s_add_i32 m0, s40, 0x1a000
	s_add_i32 s13, s40, 0x8000
	s_add_i32 s33, s40, 0xa000
	global_load_lds_dwordx4 v[2:3], off
	v_lshl_add_u64 v[2:3], v[6:7], 0, s[6:7]
	s_mov_b32 m0, s13
	s_add_u32 s4, s4, 0x80880
	global_load_lds_dwordx4 v[2:3], off
	v_lshl_add_u64 v[2:3], v[8:9], 0, s[6:7]
	s_mov_b32 m0, s33
	s_addc_u32 s5, s5, 0
	global_load_lds_dwordx4 v[2:3], off
	s_add_i32 m0, s40, 0x1c000
	v_lshl_add_u64 v[2:3], s[4:5], 0, v[132:133]
	global_load_lds_dwordx4 v[2:3], off
	v_lshl_add_u64 v[2:3], s[4:5], 0, v[130:131]
	s_add_i32 m0, s40, 0x1e000
	v_and_b32_e32 v136, 15, v143
	global_load_lds_dwordx4 v[2:3], off
	v_and_b32_e32 v10, 48, v143
	v_lshlrev_b32_e32 v11, 2, v143
	v_lshl_or_b32 v10, v136, 6, v10
	v_and_b32_e32 v11, 32, v11
	v_bitop3_b32 v1, v10, v1, v11 bitop3:0xde
	s_waitcnt vmcnt(6)
	s_add_i32 s49, 0, 0x10000
	s_add_i32 s48, 0, 0x14000
	s_add_i32 s44, 0, 0x18000
	s_add_i32 s43, 0, 0x1c000
	v_bitop3_b32 v10, v10, v12, v11 bitop3:0xde
	v_add_u32_e32 v141, s49, v1
	v_add_u32_e32 v140, s48, v1
	s_add_i32 s49, s49, s36
	s_add_i32 s48, s48, s36
	v_add_u32_e32 v139, s44, v1
	v_add_u32_e32 v138, s43, v1
	s_add_i32 s44, s44, s36
	s_add_i32 s43, s43, s36
	v_or_b32_e32 v142, s12, v136
	v_add_u32_e32 v137, 0, v10
	s_mov_b32 s53, -2
	s_mov_b64 s[4:5], 0x8c80880
	s_add_i32 s51, s40, 0xc000
	s_add_i32 s50, s40, 0xe000
	s_mov_b64 s[6:7], 0xd00900
	s_add_i32 s47, s49, 0x2000
	s_mov_b64 s[10:11], 0xd80900
	s_add_i32 s46, s48, 0x2000
	s_mov_b64 s[24:25], 0x8c00900
	s_mov_b64 s[26:27], 0x8c80900
	s_mov_b64 s[28:29], 0xd00980
	s_add_i32 s42, s44, 0x2000
	s_mov_b64 s[30:31], 0xd80980
	s_add_i32 s41, s43, 0x2000
	s_mov_b64 s[36:37], 0x8c00980
	s_mov_b64 s[38:39], s[96:97]
	v_mov_b32_e32 v134, v130
	v_mov_b32_e32 v130, v0
	v_mov_b32_e32 v0, v131
	v_mov_b32_e32 v1, v131
	v_mov_b32_e32 v2, v131
	v_mov_b32_e32 v3, v131
	v_mov_b32_e32 v4, v131
	v_mov_b32_e32 v5, v131
	v_mov_b32_e32 v6, v131
	v_mov_b32_e32 v7, v131
	v_mov_b32_e32 v8, v131
	v_mov_b32_e32 v9, v131
	v_mov_b32_e32 v10, v131
	v_mov_b32_e32 v11, v131
	v_mov_b32_e32 v12, v131
	v_mov_b32_e32 v13, v131
	v_mov_b32_e32 v14, v131
	v_mov_b32_e32 v15, v131
	v_mov_b32_e32 v16, v131
	v_mov_b32_e32 v17, v131
	v_mov_b32_e32 v18, v131
	v_mov_b32_e32 v19, v131
	v_mov_b32_e32 v20, v131
	v_mov_b32_e32 v21, v131
	v_mov_b32_e32 v22, v131
	v_mov_b32_e32 v23, v131
	v_mov_b32_e32 v24, v131
	v_mov_b32_e32 v25, v131
	v_mov_b32_e32 v26, v131
	v_mov_b32_e32 v27, v131
	v_mov_b32_e32 v28, v131
	v_mov_b32_e32 v29, v131
	v_mov_b32_e32 v30, v131
	v_mov_b32_e32 v31, v131
	v_mov_b32_e32 v32, v131
	v_mov_b32_e32 v33, v131
	v_mov_b32_e32 v34, v131
	v_mov_b32_e32 v35, v131
	v_mov_b32_e32 v36, v131
	v_mov_b32_e32 v37, v131
	v_mov_b32_e32 v38, v131
	v_mov_b32_e32 v39, v131
	v_mov_b32_e32 v40, v131
	v_mov_b32_e32 v41, v131
	v_mov_b32_e32 v42, v131
	v_mov_b32_e32 v43, v131
	v_mov_b32_e32 v44, v131
	v_mov_b32_e32 v45, v131
	v_mov_b32_e32 v46, v131
	v_mov_b32_e32 v47, v131
	v_mov_b32_e32 v48, v131
	v_mov_b32_e32 v49, v131
	v_mov_b32_e32 v50, v131
	v_mov_b32_e32 v51, v131
	v_mov_b32_e32 v52, v131
	v_mov_b32_e32 v53, v131
	v_mov_b32_e32 v54, v131
	v_mov_b32_e32 v55, v131
	v_mov_b32_e32 v56, v131
	v_mov_b32_e32 v57, v131
	v_mov_b32_e32 v58, v131
	v_mov_b32_e32 v59, v131
	v_mov_b32_e32 v60, v131
	v_mov_b32_e32 v61, v131
	v_mov_b32_e32 v62, v131
	v_mov_b32_e32 v63, v131
	v_mov_b32_e32 v64, v131
	v_mov_b32_e32 v65, v131
	v_mov_b32_e32 v66, v131
	v_mov_b32_e32 v67, v131
	v_mov_b32_e32 v68, v131
	v_mov_b32_e32 v69, v131
	v_mov_b32_e32 v70, v131
	v_mov_b32_e32 v71, v131
	v_mov_b32_e32 v72, v131
	v_mov_b32_e32 v73, v131
	v_mov_b32_e32 v74, v131
	v_mov_b32_e32 v75, v131
	v_mov_b32_e32 v76, v131
	v_mov_b32_e32 v77, v131
	v_mov_b32_e32 v78, v131
	v_mov_b32_e32 v79, v131
	v_mov_b32_e32 v80, v131
	v_mov_b32_e32 v81, v131
	v_mov_b32_e32 v82, v131
	v_mov_b32_e32 v83, v131
	v_mov_b32_e32 v84, v131
	v_mov_b32_e32 v85, v131
	v_mov_b32_e32 v86, v131
	v_mov_b32_e32 v87, v131
	v_mov_b32_e32 v88, v131
	v_mov_b32_e32 v89, v131
	v_mov_b32_e32 v90, v131
	v_mov_b32_e32 v91, v131
	v_mov_b32_e32 v92, v131
	v_mov_b32_e32 v93, v131
	v_mov_b32_e32 v94, v131
	v_mov_b32_e32 v95, v131
	v_mov_b32_e32 v96, v131
	v_mov_b32_e32 v97, v131
	v_mov_b32_e32 v98, v131
	v_mov_b32_e32 v99, v131
	v_mov_b32_e32 v100, v131
	v_mov_b32_e32 v101, v131
	v_mov_b32_e32 v102, v131
	v_mov_b32_e32 v103, v131
	v_mov_b32_e32 v104, v131
	v_mov_b32_e32 v105, v131
	v_mov_b32_e32 v106, v131
	v_mov_b32_e32 v107, v131
	v_mov_b32_e32 v108, v131
	v_mov_b32_e32 v109, v131
	v_mov_b32_e32 v110, v131
	v_mov_b32_e32 v111, v131
	v_mov_b32_e32 v112, v131
	v_mov_b32_e32 v113, v131
	v_mov_b32_e32 v114, v131
	v_mov_b32_e32 v115, v131
	v_mov_b32_e32 v116, v131
	v_mov_b32_e32 v117, v131
	v_mov_b32_e32 v118, v131
	v_mov_b32_e32 v119, v131
	v_mov_b32_e32 v120, v131
	v_mov_b32_e32 v121, v131
	v_mov_b32_e32 v122, v131
	v_mov_b32_e32 v123, v131
	v_mov_b32_e32 v124, v131
	v_mov_b32_e32 v125, v131
	v_mov_b32_e32 v126, v131
	v_mov_b32_e32 v127, v131
	s_barrier
	.p2align	6

.LBB0_874:
	s_add_i32 s63, s18, 0xf80
	ds_read_b128 v[146:149], v141
	ds_read_b128 v[150:153], v141 offset:1024
	ds_read_b128 v[154:157], v141 offset:2048
	ds_read_b128 v[158:161], v141 offset:3072
	ds_read_b128 v[162:165], v140
	ds_read_b128 v[166:169], v140 offset:1024
	ds_read_b128 v[170:173], v140 offset:2048
	ds_read_b128 v[174:177], v140 offset:3072
	s_and_b32 s63, s63, 0xf80
	s_add_u32 s63, s16, s63
	s_addc_u32 s65, s17, 0
	s_add_u32 s64, s63, 0x80000
	s_mov_b32 m0, s51
	s_addc_u32 s65, s65, 0
	ds_read_b128 v[178:181], v137
	ds_read_b128 v[182:185], v137 offset:1024
	ds_read_b128 v[186:189], v137 offset:2048
	ds_read_b128 v[190:193], v137 offset:3072
	ds_read_b128 v[194:197], v137 offset:4096
	ds_read_b128 v[198:201], v137 offset:5120
	ds_read_b128 v[202:205], v137 offset:6144
	ds_read_b128 v[206:209], v137 offset:7168
	global_load_lds_dwordx4 v130, s[64:65]
	s_mov_b32 m0, s50
	v_mov_b32_e32 v129, v131
	global_load_lds_dwordx4 v128, s[64:65]
	s_waitcnt vmcnt(8)
	s_waitcnt lgkmcnt(0)
	s_barrier
	s_setprio 1
	s_waitcnt lgkmcnt(0)
	v_mfma_f32_16x16x32_bf16 v[124:127], v[146:149], v[178:181], v[124:127]
	v_mfma_f32_16x16x32_bf16 v[120:123], v[154:157], v[178:181], v[120:123]
	v_mfma_f32_16x16x32_bf16 v[116:119], v[146:149], v[186:189], v[116:119]
	v_mfma_f32_16x16x32_bf16 v[112:115], v[154:157], v[186:189], v[112:115]
	v_mfma_f32_16x16x32_bf16 v[108:111], v[146:149], v[194:197], v[108:111]
	v_mfma_f32_16x16x32_bf16 v[104:107], v[154:157], v[194:197], v[104:107]
	v_mfma_f32_16x16x32_bf16 v[100:103], v[146:149], v[202:205], v[100:103]
	v_mfma_f32_16x16x32_bf16 v[96:99], v[154:157], v[202:205], v[96:99]
	v_mfma_f32_16x16x32_bf16 v[124:127], v[150:153], v[182:185], v[124:127]
	v_mfma_f32_16x16x32_bf16 v[120:123], v[158:161], v[182:185], v[120:123]
	v_mfma_f32_16x16x32_bf16 v[116:119], v[150:153], v[190:193], v[116:119]
	v_mfma_f32_16x16x32_bf16 v[112:115], v[158:161], v[190:193], v[112:115]
	v_mfma_f32_16x16x32_bf16 v[108:111], v[150:153], v[198:201], v[108:111]
	v_mfma_f32_16x16x32_bf16 v[104:107], v[158:161], v[198:201], v[104:107]
	v_mfma_f32_16x16x32_bf16 v[100:103], v[150:153], v[206:209], v[100:103]
	v_mfma_f32_16x16x32_bf16 v[96:99], v[158:161], v[206:209], v[96:99]
	s_setprio 0
	s_setprio 1
	v_mfma_f32_16x16x32_bf16 v[92:95], v[162:165], v[178:181], v[92:95]
	v_mfma_f32_16x16x32_bf16 v[88:91], v[170:173], v[178:181], v[88:91]
	v_mfma_f32_16x16x32_bf16 v[84:87], v[162:165], v[186:189], v[84:87]
	v_mfma_f32_16x16x32_bf16 v[80:83], v[170:173], v[186:189], v[80:83]
	v_mfma_f32_16x16x32_bf16 v[76:79], v[162:165], v[194:197], v[76:79]
	v_mfma_f32_16x16x32_bf16 v[72:75], v[170:173], v[194:197], v[72:75]
	v_mfma_f32_16x16x32_bf16 v[68:71], v[162:165], v[202:205], v[68:71]
	v_mfma_f32_16x16x32_bf16 v[64:67], v[170:173], v[202:205], v[64:67]
	v_mfma_f32_16x16x32_bf16 v[92:95], v[166:169], v[182:185], v[92:95]
	v_mfma_f32_16x16x32_bf16 v[88:91], v[174:177], v[182:185], v[88:91]
	v_mfma_f32_16x16x32_bf16 v[84:87], v[166:169], v[190:193], v[84:87]
	v_mfma_f32_16x16x32_bf16 v[80:83], v[174:177], v[190:193], v[80:83]
	v_mfma_f32_16x16x32_bf16 v[76:79], v[166:169], v[198:201], v[76:79]
	v_mfma_f32_16x16x32_bf16 v[72:75], v[174:177], v[198:201], v[72:75]
	v_mfma_f32_16x16x32_bf16 v[68:71], v[166:169], v[206:209], v[68:71]
	v_mfma_f32_16x16x32_bf16 v[64:67], v[174:177], v[206:209], v[64:67]
	s_setprio 0
	s_barrier
	s_add_u32 s64, s38, s18
	v_mov_b32_e32 v133, v131
	s_addc_u32 s65, s39, s19
	v_lshl_add_u64 v[210:211], s[64:65], 0, v[132:133]
	s_mov_b32 m0, s49
	v_lshl_add_u64 v[212:213], v[210:211], 0, s[20:21]
	v_mov_b32_e32 v135, v131
	ds_read_b128 v[178:181], v137 offset:16384
	ds_read_b128 v[182:185], v137 offset:17408
	ds_read_b128 v[186:189], v137 offset:18432
	ds_read_b128 v[190:193], v137 offset:19456
	ds_read_b128 v[194:197], v137 offset:20480
	ds_read_b128 v[198:201], v137 offset:21504
	ds_read_b128 v[202:205], v137 offset:22528
	ds_read_b128 v[206:209], v137 offset:23552
	global_load_lds_dwordx4 v[212:213], off
	v_lshl_add_u64 v[212:213], s[64:65], 0, v[134:135]
	v_lshl_add_u64 v[214:215], v[212:213], 0, s[20:21]
	s_mov_b32 m0, s47
	s_add_u32 s64, s53, s18
	global_load_lds_dwordx4 v[214:215], off
	v_lshl_add_u64 v[214:215], v[210:211], 0, s[22:23]
	s_mov_b32 m0, s48
	s_addc_u32 s65, s61, s19
	global_load_lds_dwordx4 v[214:215], off
	v_lshl_add_u64 v[214:215], v[212:213], 0, s[22:23]
	s_mov_b32 m0, s46
	s_nop 0
	global_load_lds_dwordx4 v[214:215], off
	v_lshl_add_u64 v[214:215], s[64:65], 0, v[130:131]
	v_lshl_add_u64 v[216:217], v[214:215], 0, s[24:25]
	s_mov_b32 m0, s40
	s_nop 0
	global_load_lds_dwordx4 v[216:217], off
	v_lshl_add_u64 v[216:217], s[64:65], 0, v[128:129]
	v_lshl_add_u64 v[218:219], v[216:217], 0, s[24:25]
	s_mov_b32 m0, s45
	s_nop 0
	global_load_lds_dwordx4 v[218:219], off
	s_waitcnt vmcnt(8)
	s_waitcnt lgkmcnt(0)
	s_barrier
	s_setprio 1
	s_waitcnt lgkmcnt(0)
	v_mfma_f32_16x16x32_bf16 v[60:63], v[146:149], v[178:181], v[60:63]
	v_mfma_f32_16x16x32_bf16 v[56:59], v[154:157], v[178:181], v[56:59]
	v_mfma_f32_16x16x32_bf16 v[52:55], v[146:149], v[186:189], v[52:55]
	v_mfma_f32_16x16x32_bf16 v[48:51], v[154:157], v[186:189], v[48:51]
	v_mfma_f32_16x16x32_bf16 v[44:47], v[146:149], v[194:197], v[44:47]
	v_mfma_f32_16x16x32_bf16 v[40:43], v[154:157], v[194:197], v[40:43]
	v_mfma_f32_16x16x32_bf16 v[36:39], v[146:149], v[202:205], v[36:39]
	v_mfma_f32_16x16x32_bf16 v[32:35], v[154:157], v[202:205], v[32:35]
	v_mfma_f32_16x16x32_bf16 v[60:63], v[150:153], v[182:185], v[60:63]
	v_mfma_f32_16x16x32_bf16 v[56:59], v[158:161], v[182:185], v[56:59]
	v_mfma_f32_16x16x32_bf16 v[52:55], v[150:153], v[190:193], v[52:55]
	v_mfma_f32_16x16x32_bf16 v[48:51], v[158:161], v[190:193], v[48:51]
	v_mfma_f32_16x16x32_bf16 v[44:47], v[150:153], v[198:201], v[44:47]
	v_mfma_f32_16x16x32_bf16 v[40:43], v[158:161], v[198:201], v[40:43]
	v_mfma_f32_16x16x32_bf16 v[36:39], v[150:153], v[206:209], v[36:39]
	v_mfma_f32_16x16x32_bf16 v[32:35], v[158:161], v[206:209], v[32:35]
	s_setprio 0
	s_setprio 1
	v_mfma_f32_16x16x32_bf16 v[28:31], v[162:165], v[178:181], v[28:31]
	v_mfma_f32_16x16x32_bf16 v[24:27], v[170:173], v[178:181], v[24:27]
	v_mfma_f32_16x16x32_bf16 v[20:23], v[162:165], v[186:189], v[20:23]
	v_mfma_f32_16x16x32_bf16 v[16:19], v[170:173], v[186:189], v[16:19]
	v_mfma_f32_16x16x32_bf16 v[12:15], v[162:165], v[194:197], v[12:15]
	v_mfma_f32_16x16x32_bf16 v[8:11], v[170:173], v[194:197], v[8:11]
	v_mfma_f32_16x16x32_bf16 v[4:7], v[162:165], v[202:205], v[4:7]
	v_mfma_f32_16x16x32_bf16 v[0:3], v[170:173], v[202:205], v[0:3]
	v_mfma_f32_16x16x32_bf16 v[28:31], v[166:169], v[182:185], v[28:31]
	v_mfma_f32_16x16x32_bf16 v[24:27], v[174:177], v[182:185], v[24:27]
	v_mfma_f32_16x16x32_bf16 v[20:23], v[166:169], v[190:193], v[20:23]
	v_mfma_f32_16x16x32_bf16 v[16:19], v[174:177], v[190:193], v[16:19]
	v_mfma_f32_16x16x32_bf16 v[12:15], v[166:169], v[198:201], v[12:15]
	v_mfma_f32_16x16x32_bf16 v[8:11], v[174:177], v[198:201], v[8:11]
	v_mfma_f32_16x16x32_bf16 v[4:7], v[166:169], v[206:209], v[4:7]
	v_mfma_f32_16x16x32_bf16 v[0:3], v[174:177], v[206:209], v[0:3]
	s_setprio 0
	s_barrier
	ds_read_b128 v[146:149], v139
	ds_read_b128 v[150:153], v139 offset:1024
	ds_read_b128 v[154:157], v139 offset:2048
	ds_read_b128 v[158:161], v139 offset:3072
	ds_read_b128 v[162:165], v138
	ds_read_b128 v[166:169], v138 offset:1024
	ds_read_b128 v[170:173], v138 offset:2048
	ds_read_b128 v[174:177], v138 offset:3072
	s_mov_b32 m0, s34
	v_lshl_add_u64 v[218:219], v[214:215], 0, s[26:27]
	ds_read_b128 v[178:181], v137 offset:32768
	ds_read_b128 v[182:185], v137 offset:33792
	ds_read_b128 v[186:189], v137 offset:34816
	ds_read_b128 v[190:193], v137 offset:35840
	ds_read_b128 v[194:197], v137 offset:36864
	ds_read_b128 v[198:201], v137 offset:37888
	ds_read_b128 v[202:205], v137 offset:38912
	ds_read_b128 v[206:209], v137 offset:39936
	global_load_lds_dwordx4 v[218:219], off
	v_lshl_add_u64 v[218:219], v[216:217], 0, s[26:27]
	s_mov_b32 m0, s35
	s_nop 0
	global_load_lds_dwordx4 v[218:219], off
	s_waitcnt vmcnt(8)
	s_waitcnt lgkmcnt(0)
	s_barrier
	s_setprio 1
	s_waitcnt lgkmcnt(0)
	v_mfma_f32_16x16x32_bf16 v[124:127], v[146:149], v[178:181], v[124:127]
	v_mfma_f32_16x16x32_bf16 v[120:123], v[154:157], v[178:181], v[120:123]
	v_mfma_f32_16x16x32_bf16 v[116:119], v[146:149], v[186:189], v[116:119]
	v_mfma_f32_16x16x32_bf16 v[112:115], v[154:157], v[186:189], v[112:115]
	v_mfma_f32_16x16x32_bf16 v[108:111], v[146:149], v[194:197], v[108:111]
	v_mfma_f32_16x16x32_bf16 v[104:107], v[154:157], v[194:197], v[104:107]
	v_mfma_f32_16x16x32_bf16 v[100:103], v[146:149], v[202:205], v[100:103]
	v_mfma_f32_16x16x32_bf16 v[96:99], v[154:157], v[202:205], v[96:99]
	v_mfma_f32_16x16x32_bf16 v[124:127], v[150:153], v[182:185], v[124:127]
	v_mfma_f32_16x16x32_bf16 v[120:123], v[158:161], v[182:185], v[120:123]
	v_mfma_f32_16x16x32_bf16 v[116:119], v[150:153], v[190:193], v[116:119]
	v_mfma_f32_16x16x32_bf16 v[112:115], v[158:161], v[190:193], v[112:115]
	v_mfma_f32_16x16x32_bf16 v[108:111], v[150:153], v[198:201], v[108:111]
	v_mfma_f32_16x16x32_bf16 v[104:107], v[158:161], v[198:201], v[104:107]
	v_mfma_f32_16x16x32_bf16 v[100:103], v[150:153], v[206:209], v[100:103]
	v_mfma_f32_16x16x32_bf16 v[96:99], v[158:161], v[206:209], v[96:99]
	s_setprio 0
	s_setprio 1
	v_mfma_f32_16x16x32_bf16 v[92:95], v[162:165], v[178:181], v[92:95]
	v_mfma_f32_16x16x32_bf16 v[88:91], v[170:173], v[178:181], v[88:91]
	v_mfma_f32_16x16x32_bf16 v[84:87], v[162:165], v[186:189], v[84:87]
	v_mfma_f32_16x16x32_bf16 v[80:83], v[170:173], v[186:189], v[80:83]
	v_mfma_f32_16x16x32_bf16 v[76:79], v[162:165], v[194:197], v[76:79]
	v_mfma_f32_16x16x32_bf16 v[72:75], v[170:173], v[194:197], v[72:75]
	v_mfma_f32_16x16x32_bf16 v[68:71], v[162:165], v[202:205], v[68:71]
	v_mfma_f32_16x16x32_bf16 v[64:67], v[170:173], v[202:205], v[64:67]
	v_mfma_f32_16x16x32_bf16 v[92:95], v[166:169], v[182:185], v[92:95]
	v_mfma_f32_16x16x32_bf16 v[88:91], v[174:177], v[182:185], v[88:91]
	v_mfma_f32_16x16x32_bf16 v[84:87], v[166:169], v[190:193], v[84:87]
	v_mfma_f32_16x16x32_bf16 v[80:83], v[174:177], v[190:193], v[80:83]
	v_mfma_f32_16x16x32_bf16 v[76:79], v[166:169], v[198:201], v[76:79]
	v_mfma_f32_16x16x32_bf16 v[72:75], v[174:177], v[198:201], v[72:75]
	v_mfma_f32_16x16x32_bf16 v[68:71], v[166:169], v[206:209], v[68:71]
	v_mfma_f32_16x16x32_bf16 v[64:67], v[174:177], v[206:209], v[64:67]
	s_setprio 0
	s_barrier
; template <int ROT, class Epi0, class Epi1, class Late, class Post0>
; __device__ __forceinline__ void gemm_phase_pair(PG8_LAS unsigned char* lds, const Gemm g0, const Gemm g1, const Unit u, const Epi0& E0, const Epi1& E1, int wid_in, const Late& late, const Post0& post0) {
;     ...
;     const int t_late = ROT != 0 ? nt0 - ROT - 2 : 0;
;     for (int t = 0; t < t_late; t += 2) {
;         const char* a1 = cA + PG8_KT(t + 1); const char* a2 = cA + PG8_KT(t + 2); const char* b2 = cB + PG8_KT(t + 2); const char* a3 = cA + PG8_KT(t + 3); const char* b3 = cB + PG8_KT(t + 3);
;         PG8_PAIR_ITER(a1 + hs0, vA0, a2, b2, a3, b3, vA0, vB0, hs0);
	s_mov_b32 m0, s44
	v_lshl_add_u64 v[218:219], v[210:211], 0, s[28:29]
	ds_read_b128 v[178:181], v137 offset:49152
	ds_read_b128 v[182:185], v137 offset:50176
	ds_read_b128 v[186:189], v137 offset:51200
	ds_read_b128 v[190:193], v137 offset:52224
	ds_read_b128 v[194:197], v137 offset:53248
	ds_read_b128 v[198:201], v137 offset:54272
	ds_read_b128 v[202:205], v137 offset:55296
	ds_read_b128 v[206:209], v137 offset:56320
	global_load_lds_dwordx4 v[218:219], off
	v_lshl_add_u64 v[218:219], v[212:213], 0, s[28:29]
	s_mov_b32 m0, s42
	v_lshl_add_u64 v[210:211], v[210:211], 0, s[30:31]
	global_load_lds_dwordx4 v[218:219], off
	s_mov_b32 m0, s43
	s_nop 0
	global_load_lds_dwordx4 v[210:211], off
	v_lshl_add_u64 v[210:211], v[212:213], 0, s[30:31]
	s_mov_b32 m0, s41
	s_nop 0
	global_load_lds_dwordx4 v[210:211], off
	v_lshl_add_u64 v[210:211], v[214:215], 0, s[36:37]
	s_mov_b32 m0, s13
	s_nop 0
	global_load_lds_dwordx4 v[210:211], off
	v_lshl_add_u64 v[210:211], v[216:217], 0, s[36:37]
	s_mov_b32 m0, s33
	s_nop 0
	global_load_lds_dwordx4 v[210:211], off
	s_waitcnt vmcnt(8)
	s_waitcnt lgkmcnt(0)
	s_barrier
	s_setprio 1
	s_waitcnt lgkmcnt(0)
	v_mfma_f32_16x16x32_bf16 v[60:63], v[146:149], v[178:181], v[60:63]
	v_mfma_f32_16x16x32_bf16 v[56:59], v[154:157], v[178:181], v[56:59]
	v_mfma_f32_16x16x32_bf16 v[52:55], v[146:149], v[186:189], v[52:55]
	v_mfma_f32_16x16x32_bf16 v[48:51], v[154:157], v[186:189], v[48:51]
	v_mfma_f32_16x16x32_bf16 v[44:47], v[146:149], v[194:197], v[44:47]
	v_mfma_f32_16x16x32_bf16 v[40:43], v[154:157], v[194:197], v[40:43]
	v_mfma_f32_16x16x32_bf16 v[36:39], v[146:149], v[202:205], v[36:39]
	v_mfma_f32_16x16x32_bf16 v[32:35], v[154:157], v[202:205], v[32:35]
	v_mfma_f32_16x16x32_bf16 v[60:63], v[150:153], v[182:185], v[60:63]
	v_mfma_f32_16x16x32_bf16 v[56:59], v[158:161], v[182:185], v[56:59]
	v_mfma_f32_16x16x32_bf16 v[52:55], v[150:153], v[190:193], v[52:55]
	v_mfma_f32_16x16x32_bf16 v[48:51], v[158:161], v[190:193], v[48:51]
	v_mfma_f32_16x16x32_bf16 v[44:47], v[150:153], v[198:201], v[44:47]
	v_mfma_f32_16x16x32_bf16 v[40:43], v[158:161], v[198:201], v[40:43]
	v_mfma_f32_16x16x32_bf16 v[36:39], v[150:153], v[206:209], v[36:39]
	v_mfma_f32_16x16x32_bf16 v[32:35], v[158:161], v[206:209], v[32:35]
	s_setprio 0
	s_setprio 1
	v_mfma_f32_16x16x32_bf16 v[28:31], v[162:165], v[178:181], v[28:31]
	v_mfma_f32_16x16x32_bf16 v[24:27], v[170:173], v[178:181], v[24:27]
	v_mfma_f32_16x16x32_bf16 v[20:23], v[162:165], v[186:189], v[20:23]
	v_mfma_f32_16x16x32_bf16 v[16:19], v[170:173], v[186:189], v[16:19]
	v_mfma_f32_16x16x32_bf16 v[12:15], v[162:165], v[194:197], v[12:15]
	v_mfma_f32_16x16x32_bf16 v[8:11], v[170:173], v[194:197], v[8:11]
	v_mfma_f32_16x16x32_bf16 v[4:7], v[162:165], v[202:205], v[4:7]
	v_mfma_f32_16x16x32_bf16 v[0:3], v[170:173], v[202:205], v[0:3]
	v_mfma_f32_16x16x32_bf16 v[28:31], v[166:169], v[182:185], v[28:31]
	v_mfma_f32_16x16x32_bf16 v[24:27], v[174:177], v[182:185], v[24:27]
	v_mfma_f32_16x16x32_bf16 v[20:23], v[166:169], v[190:193], v[20:23]
	v_mfma_f32_16x16x32_bf16 v[16:19], v[174:177], v[190:193], v[16:19]
	v_mfma_f32_16x16x32_bf16 v[12:15], v[166:169], v[198:201], v[12:15]
	v_mfma_f32_16x16x32_bf16 v[8:11], v[174:177], v[198:201], v[8:11]
	v_mfma_f32_16x16x32_bf16 v[4:7], v[166:169], v[206:209], v[4:7]
	v_mfma_f32_16x16x32_bf16 v[0:3], v[174:177], v[206:209], v[0:3]
	s_setprio 0
	s_barrier
	s_add_i32 s62, s62, 2
	s_add_u32 s18, s18, 0x100
	s_addc_u32 s19, s19, 0
	s_cmp_gt_u32 s62, 27
	s_cbranch_scc1 .LBB0_877
	.p2align	6

; #define PG8_BAR __builtin_amdgcn_s_barrier()
; #define PG8_MK_V1(vA1, vB1) unsigned vA1[2], vB1[2]; { const int tid1_ = wid * 64 + hw_lane(); _Pragma("unroll") for (int i = 0; i < 2; ++i) { int R, C; stage_rc(tid1_ * 16 + i * 8192, R, C); \
;         const int Rb1 = Epi1::PERM ? ((R & ~31) + perm32(R & 31)) : R; vA1[i] = (unsigned)(R * K1 + C) * 2u; vB1[i] = (unsigned)(Rb1 * K1 + C) * 2u; } }
; template <int ROT, class Epi0, class Epi1, class Late, class Post0>
; __device__ __forceinline__ void gemm_phase_pair(PG8_LAS unsigned char* lds, const Gemm g0, const Gemm g1, const Unit u, const Epi0& E0, const Epi1& E1, int wid_in, const Late& late, const Post0& post0) {
;     ...
;     if (wr == 1) PG8_BAR;
;     PG8_MK_V1(vA1, vB1)
;     for (int t = 0; t < nt1 - 2; t += 2) {
;         const char* a1 = nA + (size_t)(t + 1) * kstep; const char* a2 = nA + (size_t)(t + 2) * kstep; const char* b2 = nB + (size_t)(t + 2) * kstep;
;         PG8_PAIR_ITER(a1 + hs1, vA1, a2, b2, a2 + kstep, b2 + kstep, vA1, vB1, hs1);
.LBB0_884:
	s_and_b64 vcc, exec, s[0:1]
	s_cbranch_vccnz .LBB0_886
	s_barrier
	.p2align	6

; template <class Epi, class Sched, bool ALIGN_EPI = false, bool SP2 = false>
; __device__ __forceinline__ void gemm_phase(PG8_LAS unsigned char* lds, const Gemm g, const Sched& S, const Epi& E, int wid_in) {
;     ...
;         const bool has_next = S.next(ui + 1, nxt);
;         const char* nA = has_next ? (const char*)g.A + (size_t)nxt.pm * tstep : cA; const char* nB = has_next ? (const char*)g.Bt + (size_t)nxt.pn * tstep : cB;
;         for (int t = 0; t < nt; t += 2) {
;             const bool last = (t == nt - 2);
;             if constexpr (Epi::HAS_MID) { if (t == nt / 2) E.mid(acc, cur, wr, wc, fr, fq); }
;             const char* a1 = cA + (size_t)(t + 1) * kstep;
;             const char* a2 = last ? nA : cA + (size_t)(t + 2) * kstep; const char* b2 = last ? nB : cB + (size_t)(t + 2) * kstep;
.LBB0_985:
	s_add_u32 s23, s26, 0x100
	s_addc_u32 s45, s27, 0
	s_ashr_i32 s19, s18, 31
	s_lshl_b64 s[20:21], s[18:19], 19
	s_add_u32 s24, s8, s20
	s_addc_u32 s25, s9, s21
	s_and_b64 s[20:21], s[2:3], exec
	s_cselect_b32 s19, s25, s11
	s_cselect_b32 s46, s24, s10
	s_ashr_i32 s17, s16, 31
	s_lshl_b64 s[20:21], s[16:17], 19
	s_add_u32 s20, s33, s20
	s_addc_u32 s21, s34, s21
	s_and_b64 s[28:29], s[2:3], exec
	s_cselect_b32 s17, s21, s27
	s_cselect_b32 s47, s20, s26
	v_lshl_add_u64 v[144:145], s[10:11], 0, v[136:137]
	v_lshl_add_u64 v[146:147], s[10:11], 0, v[138:139]
	s_mov_b32 s48, -2
	s_mov_b64 s[26:27], 0
	.p2align	6
